# speedup vs baseline: 1.0047x; 1.0047x over previous
; __device__ __forceinline__ void row_coef_load(RowCoef& rc, const float* gA, const float* gate, const float* gB, const float* scale,
;                                               const float* shift, int lane) {
; #pragma unroll
;   for (int i = 0; i < 8; ++i) {
;     const int c = (i * 64 + lane) * 4;
;     rc.cA[i] = f32x4{0.f, 0.f, 0.f, 0.f};
;     rc.cB[i] = f32x4{0.f, 0.f, 0.f, 0.f};
;     rc.cS[i] = f32x4{0.f, 0.f, 0.f, 0.f};
;     if (gA != nullptr) rc.cA[i] = *(const f32x4*)(gA + c) * *(const f32x4*)(gate + c);
;     if (gB != nullptr) {
;       rc.cB[i] = *(const f32x4*)(gB + c) * (*(const f32x4*)(scale + c) + 1.f);
;       rc.cS[i] = *(const f32x4*)(shift + c);
;     }
;   }
; }
; __device__ __forceinline__ void run_phase(const Params& p, int ph, bf16_t* lds, const int wave0) {
;     ...
;     RowCoef rc;
;     row_coef_load(rc, ng + 2048, mod + 2 * 2048, ng + 2 * 2048, mod + 4 * 2048, mod + 3 * 2048, lane);
;     {
;       RowData cur, nxt;
;       int row = bid * 4 + wave;
;       row_load(cur, xin + (long)row * 2048, y + (long)row * 2048, lane);
;       for (; row < S_; row += nb * 4) {
;         const int nrow = row + nb * 4;
;         if (nrow < S_) row_load(nxt, xin + (long)nrow * 2048, y + (long)nrow * 2048, lane);
.LBB0_303:
	s_lshl_b32 s0, s33, 2
	s_add_i32 s0, s0, s25
	s_cmpk_gt_i32 s0, 0x3fff
	s_cbranch_scc1 .LBB0_313
	s_ashr_i32 s1, s0, 31
	v_readlane_b32 s52, v253, 16
	s_lshl_b64 s[6:7], s[0:1], 13
	v_readlane_b32 s66, v253, 30
	v_readlane_b32 s67, v253, 31
	s_add_u32 s6, s66, s6
	s_addc_u32 s7, s67, s7
	s_lshl_b64 s[8:9], s[0:1], 12
	s_add_u32 s10, s92, s8
	s_addc_u32 s11, s93, s9
	v_lshlrev_b32_e32 v131, 1, v0
	global_load_dwordx4 v[74:77], v74, s[6:7]
	s_nop 0
	global_load_dwordx4 v[78:81], v78, s[6:7]
	s_nop 0
	global_load_dwordx4 v[82:85], v82, s[6:7]
	s_nop 0
	global_load_dwordx4 v[94:97], v94, s[6:7]
	s_nop 0
	global_load_dwordx2 v[196:197], v131, s[10:11] offset:3584
	global_load_dwordx2 v[198:199], v131, s[10:11] offset:3072
	global_load_dwordx2 v[200:201], v131, s[10:11] offset:2560
	global_load_dwordx2 v[202:203], v131, s[10:11] offset:2048
	global_load_dwordx4 v[98:101], v110, s[6:7] offset:3072
	global_load_dwordx4 v[102:105], v110, s[6:7] offset:2048
	global_load_dwordx4 v[106:109], v110, s[6:7] offset:1024
	s_nop 0
	global_load_dwordx4 v[110:113], v110, s[6:7]
	s_nop 0
	global_load_dwordx2 v[204:205], v131, s[10:11] offset:1536
	global_load_dwordx2 v[206:207], v131, s[10:11] offset:1024
	global_load_dwordx2 v[208:209], v131, s[10:11] offset:512
	global_load_dwordx2 v[210:211], v131, s[10:11]
	s_add_u32 s8, s84, s8
	v_readlane_b32 s18, v255, 14
	s_addc_u32 s9, s85, s9
	s_add_i32 s1, s18, s25
	s_lshl_b32 s10, s17, 3
	s_add_i32 s1, s1, s10
	s_lshl_b32 s10, s24, 2
	s_add_i32 s12, s1, s10
	s_ashr_i32 s13, s12, 31
	s_lshl_b64 s[10:11], s[12:13], 13
	s_add_u32 s10, s66, s10
	s_addc_u32 s11, s67, s11
	s_lshl_b64 s[12:13], s[12:13], 12
	s_add_u32 s12, s84, s12
	s_waitcnt vmcnt(16)
	v_pk_mul_f32 v[124:125], v[124:125], v[128:129]
	v_pk_mul_f32 v[122:123], v[122:123], v[126:127]
	v_pk_mul_f32 v[116:117], v[116:117], v[120:121]
	v_pk_mul_f32 v[114:115], v[114:115], v[118:119]
	v_pk_mul_f32 v[118:119], v[88:89], v[92:93]
	v_pk_mul_f32 v[120:121], v[86:87], v[90:91]
	v_pk_mul_f32 v[126:127], v[68:69], v[72:73]
	v_pk_mul_f32 v[128:129], v[66:67], v[70:71]
	v_pk_mul_f32 v[164:165], v[60:61], v[64:65]
	v_pk_mul_f32 v[166:167], v[58:59], v[62:63]
	v_pk_mul_f32 v[168:169], v[52:53], v[56:57]
	v_pk_mul_f32 v[170:171], v[50:51], v[54:55]
	v_pk_mul_f32 v[172:173], v[44:45], v[48:49]
	v_pk_mul_f32 v[174:175], v[42:43], v[46:47]
	v_pk_mul_f32 v[176:177], v[36:37], v[40:41]
	v_pk_mul_f32 v[178:179], v[34:35], v[38:39]
	v_xor_b32_e32 v227, 0x80, v0
	v_xor_b32_e32 v228, 64, v0
	v_xor_b32_e32 v229, 32, v0
	v_xor_b32_e32 v230, 16, v0
	v_xor_b32_e32 v231, 8, v0
	v_xor_b32_e32 v232, 4, v0
	v_lshlrev_b32_e32 v0, 3, v223
	v_mov_b32_e32 v131, v1
	s_addc_u32 s13, s85, s13
	s_movk_i32 s1, 0x1000
	s_mov_b32 s17, 0x800000
	v_readlane_b32 s53, v253, 17
	v_readlane_b32 s54, v253, 18
	v_readlane_b32 s55, v253, 19
	v_readlane_b32 s56, v253, 20
	v_readlane_b32 s57, v253, 21
	v_readlane_b32 s58, v253, 22
	v_readlane_b32 s59, v253, 23
	v_readlane_b32 s60, v253, 24
	v_readlane_b32 s61, v253, 25
	v_readlane_b32 s62, v253, 26
	v_readlane_b32 s63, v253, 27
	v_readlane_b32 s64, v253, 28
	v_readlane_b32 s65, v253, 29
	v_readlane_b32 s19, v255, 15
	s_waitcnt vmcnt(0)
	s_branch .LBB0_306

; __device__ __forceinline__ void row_post(const RowData& rd, float* xout, const RowCoef& rc, const bool has_h, bf16_t* hrow, int lane) {
;   f32x4 xv[8], yv[8];
;   float ss = 0.f;
; #pragma unroll
;   for (int i = 0; i < 8; ++i) {
;     const u32x2 yw = rd.y[i];
;     yv[i] = f32x4{__uint_as_float(yw[0] << 16), __uint_as_float(yw[0] & 0xffff0000u), __uint_as_float(yw[1] << 16),
;                   __uint_as_float(yw[1] & 0xffff0000u)};
;     ss += yv[i][0] * yv[i][0] + yv[i][1] * yv[i][1] + yv[i][2] * yv[i][2] + yv[i][3] * yv[i][3];
;   }
;   ss = wave_sum(ss, lane);
;   const float invy = rsqrtf(ss * (1.f / 2048.f) + 1e-6f);
;   float sx = 0.f;
; #pragma unroll
;   for (int i = 0; i < 8; ++i) {
;     const int c = (i * 64 + lane) * 4;
;     const f32x4 xn = rd.x[i] + (yv[i] * invy) * rc.cA[i];
;     xv[i] = xn;
;     *(f32x4*)(xout + c) = xn;
;     sx += xn[0] * xn[0] + xn[1] * xn[1] + xn[2] * xn[2] + xn[3] * xn[3];
;   }
.LBB0_308:
	v_and_b32_e32 v67, 0xffff0000, v210
	v_and_b32_e32 v71, 0xffff0000, v208
	v_lshlrev_b32_e32 v66, 16, v210
	v_mul_f32_e32 v86, v67, v67
	v_lshlrev_b32_e32 v70, 16, v208
	v_mul_f32_e32 v87, v71, v71
	v_lshlrev_b32_e32 v68, 16, v211
	v_fmac_f32_e32 v86, v66, v66
	v_lshlrev_b32_e32 v72, 16, v209
	v_fmac_f32_e32 v87, v70, v70
	v_and_b32_e32 v69, 0xffff0000, v211
	v_fmac_f32_e32 v86, v68, v68
	v_and_b32_e32 v73, 0xffff0000, v209
	v_fmac_f32_e32 v87, v72, v72
	v_fmac_f32_e32 v86, v69, v69
	v_fmac_f32_e32 v87, v73, v73
	v_and_b32_e32 v91, 0xffff0000, v206
	v_add_f32_e32 v86, v86, v87
	v_lshlrev_b32_e32 v90, 16, v206
	v_mul_f32_e32 v87, v91, v91
	v_lshlrev_b32_e32 v92, 16, v207
	v_fmac_f32_e32 v87, v90, v90
	v_and_b32_e32 v93, 0xffff0000, v207
	v_fmac_f32_e32 v87, v92, v92
	v_fmac_f32_e32 v87, v93, v93
	v_and_b32_e32 v207, 0xffff0000, v204
	v_add_f32_e32 v86, v87, v86
	v_lshlrev_b32_e32 v206, 16, v204
	v_mul_f32_e32 v87, v207, v207
	v_lshlrev_b32_e32 v204, 16, v205
	v_fmac_f32_e32 v87, v206, v206
	v_and_b32_e32 v205, 0xffff0000, v205
	v_fmac_f32_e32 v87, v204, v204
	v_fmac_f32_e32 v87, v205, v205
	v_and_b32_e32 v211, 0xffff0000, v202
	v_and_b32_e32 v210, 0xffff0000, v200
	v_add_f32_e32 v88, v87, v86
	v_lshlrev_b32_e32 v209, 16, v202
	v_lshlrev_b32_e32 v208, 16, v200
	v_pk_mul_f32 v[86:87], v[210:211], v[210:211]
	v_lshlrev_b32_e32 v219, 16, v203
	v_lshlrev_b32_e32 v218, 16, v201
	v_pk_fma_f32 v[86:87], v[208:209], v[208:209], v[86:87]
	v_and_b32_e32 v203, 0xffff0000, v203
	v_and_b32_e32 v202, 0xffff0000, v201
	v_pk_fma_f32 v[86:87], v[218:219], v[218:219], v[86:87]
	v_and_b32_e32 v221, 0xffff0000, v198
	v_pk_fma_f32 v[86:87], v[202:203], v[202:203], v[86:87]
	v_and_b32_e32 v220, 0xffff0000, v196
	v_add_f32_e32 v87, v87, v88
	v_add_f32_e32 v88, v86, v87
	v_lshlrev_b32_e32 v201, 16, v198
	v_lshlrev_b32_e32 v200, 16, v196
	v_pk_mul_f32 v[86:87], v[220:221], v[220:221]
	v_lshlrev_b32_e32 v235, 16, v199
	v_lshlrev_b32_e32 v234, 16, v197
	v_pk_fma_f32 v[86:87], v[200:201], v[200:201], v[86:87]
	v_and_b32_e32 v199, 0xffff0000, v199
	v_and_b32_e32 v198, 0xffff0000, v197
	v_pk_fma_f32 v[86:87], v[234:235], v[234:235], v[86:87]
	s_nop 0
	v_pk_fma_f32 v[86:87], v[198:199], v[198:199], v[86:87]
	s_nop 0
	v_add_f32_e32 v87, v87, v88
	v_add_f32_e32 v86, v86, v87
	ds_bpermute_b32 v87, v227, v86
	s_waitcnt lgkmcnt(0)
	v_add_f32_e32 v86, v86, v87
	ds_bpermute_b32 v87, v228, v86
	s_waitcnt lgkmcnt(0)
	v_add_f32_e32 v86, v86, v87
	ds_bpermute_b32 v87, v229, v86
	s_waitcnt lgkmcnt(0)
	v_add_f32_e32 v86, v86, v87
	ds_bpermute_b32 v87, v230, v86
	s_waitcnt lgkmcnt(0)
	v_add_f32_e32 v86, v86, v87
	ds_bpermute_b32 v87, v231, v86
	s_waitcnt lgkmcnt(0)
	v_add_f32_e32 v86, v86, v87
	ds_bpermute_b32 v87, v232, v86
	s_waitcnt lgkmcnt(0)
	v_add_f32_e32 v86, v86, v87
	v_fmamk_f32 v86, v86, 0x3a000000, v214
	v_mul_f32_e32 v87, 0x4b800000, v86
	v_cmp_gt_f32_e32 vcc, s17, v86
	s_nop 1
	v_cndmask_b32_e32 v86, v86, v87, vcc
	v_rsq_f32_e32 v86, v86
	s_nop 0
	v_mul_f32_e32 v87, 0x45800000, v86
	v_cndmask_b32_e32 v196, v86, v87, vcc
	v_pk_mul_f32 v[68:69], v[68:69], v[196:197] op_sel_hi:[1,0]
	v_pk_mul_f32 v[66:67], v[66:67], v[196:197] op_sel_hi:[1,0]
	v_pk_fma_f32 v[88:89], v[176:177], v[68:69], v[112:113]
	v_pk_mul_f32 v[68:69], v[72:73], v[196:197] op_sel_hi:[1,0]
	v_pk_mul_f32 v[72:73], v[92:93], v[196:197] op_sel_hi:[1,0]
	v_pk_mul_f32 v[92:93], v[204:205], v[196:197] op_sel_hi:[1,0]
	v_pk_fma_f32 v[86:87], v[178:179], v[66:67], v[110:111]
	v_pk_mul_f32 v[66:67], v[70:71], v[196:197] op_sel_hi:[1,0]
	v_pk_mul_f32 v[70:71], v[90:91], v[196:197] op_sel_hi:[1,0]
	v_pk_mul_f32 v[90:91], v[206:207], v[196:197] op_sel_hi:[1,0]
	v_pk_fma_f32 v[92:93], v[164:165], v[92:93], v[100:101]
	v_mov_b32_e32 v100, v219
	v_mov_b32_e32 v101, v203
	v_pk_fma_f32 v[90:91], v[166:167], v[90:91], v[98:99]
	v_mov_b32_e32 v98, v209
	v_pk_mul_f32 v[100:101], v[100:101], v[196:197] op_sel_hi:[1,0]
	v_mov_b32_e32 v209, v210
	v_mov_b32_e32 v219, v202
	v_pk_fma_f32 v[70:71], v[170:171], v[70:71], v[102:103]
	v_mov_b32_e32 v99, v211
	v_pk_fma_f32 v[96:97], v[126:127], v[100:101], v[96:97]
	v_pk_mul_f32 v[100:101], v[208:209], v[196:197] op_sel_hi:[1,0]
	v_pk_mul_f32 v[102:103], v[218:219], v[196:197] op_sel_hi:[1,0]
	v_lshl_add_u64 v[110:111], s[6:7], 0, v[130:131]
	v_pk_mul_f32 v[98:99], v[98:99], v[196:197] op_sel_hi:[1,0]
	v_pk_fma_f32 v[84:85], v[118:119], v[102:103], v[84:85]
	v_pk_fma_f32 v[82:83], v[120:121], v[100:101], v[82:83]
	v_mov_b32_e32 v100, v201
	v_mov_b32_e32 v101, v221
	v_mov_b32_e32 v102, v235
	v_mov_b32_e32 v103, v199
	v_pk_fma_f32 v[94:95], v[128:129], v[98:99], v[94:95]
	v_add_co_u32_e32 v98, vcc, s1, v110
	v_pk_mul_f32 v[100:101], v[100:101], v[196:197] op_sel_hi:[1,0]
	v_pk_mul_f32 v[102:103], v[102:103], v[196:197] op_sel_hi:[1,0]
	v_mov_b32_e32 v201, v220
	v_mov_b32_e32 v235, v198
	v_addc_co_u32_e32 v99, vcc, 0, v111, vcc
	v_pk_fma_f32 v[80:81], v[116:117], v[102:103], v[80:81]
	v_pk_fma_f32 v[78:79], v[114:115], v[100:101], v[78:79]
	v_pk_mul_f32 v[100:101], v[200:201], v[196:197] op_sel_hi:[1,0]
	v_pk_mul_f32 v[102:103], v[234:235], v[196:197] op_sel_hi:[1,0]
	v_pk_fma_f32 v[68:69], v[172:173], v[68:69], v[108:109]
	v_pk_fma_f32 v[66:67], v[174:175], v[66:67], v[106:107]
	v_pk_fma_f32 v[72:73], v[168:169], v[72:73], v[104:105]
	v_pk_fma_f32 v[76:77], v[124:125], v[102:103], v[76:77]
	v_pk_fma_f32 v[74:75], v[122:123], v[100:101], v[74:75]
	s_andn2_b64 vcc, exec, s[4:5]
	global_store_dwordx4 v[110:111], v[86:89], off
	global_store_dwordx4 v[110:111], v[66:69], off offset:1024
	global_store_dwordx4 v[110:111], v[70:73], off offset:2048
	global_store_dwordx4 v[110:111], v[90:93], off offset:3072
	global_store_dwordx4 v[98:99], v[94:97], off
	global_store_dwordx4 v[98:99], v[82:85], off offset:1024
	global_store_dwordx4 v[98:99], v[78:81], off offset:2048
	global_store_dwordx4 v[98:99], v[74:77], off offset:3072
	s_waitcnt vmcnt(8)
	s_cbranch_vccnz .LBB0_305
; __device__ __forceinline__ void row_post(const RowData& rd, float* xout, const RowCoef& rc, const bool has_h, bf16_t* hrow, int lane) {
;     ...
;   if (has_h) {
;     sx = wave_sum(sx, lane);
;     const float inv = rsqrtf(sx * (1.f / 2048.f) + 1e-6f);
; #pragma unroll
;     for (int i = 0; i < 8; ++i) {
;       const int c = (i * 64 + lane) * 4;
;       const f32x4 hv = xv[i] * inv * rc.cB[i] + rc.cS[i];
;       u32x2 w;
;       w[0] = pack2(hv[0], hv[1]);
;       w[1] = pack2(hv[2], hv[3]);
;       *(u32x2*)(hrow + c) = w;
;     }
;   }
	v_mul_f32_e32 v98, v87, v87
	v_mul_f32_e32 v99, v67, v67
	v_fmac_f32_e32 v98, v86, v86
	v_fmac_f32_e32 v99, v66, v66
	v_fmac_f32_e32 v98, v88, v88
	v_fmac_f32_e32 v99, v68, v68
	v_fmac_f32_e32 v98, v89, v89
	v_fmac_f32_e32 v99, v69, v69
	v_add_f32_e32 v98, v98, v99
	v_mul_f32_e32 v99, v71, v71
	v_fmac_f32_e32 v99, v70, v70
	v_fmac_f32_e32 v99, v72, v72
	v_fmac_f32_e32 v99, v73, v73
	v_add_f32_e32 v98, v99, v98
	v_mul_f32_e32 v99, v91, v91
	v_fmac_f32_e32 v99, v90, v90
	v_mov_b32_e32 v104, v83
	v_mov_b32_e32 v105, v95
	v_fmac_f32_e32 v99, v92, v92
	v_mov_b32_e32 v102, v82
	v_mov_b32_e32 v103, v94
	v_pk_mul_f32 v[104:105], v[104:105], v[104:105]
	v_fmac_f32_e32 v99, v93, v93
	v_mov_b32_e32 v100, v84
	v_mov_b32_e32 v101, v96
	v_pk_fma_f32 v[102:103], v[102:103], v[102:103], v[104:105]
	v_add_f32_e32 v106, v99, v98
	v_mov_b32_e32 v98, v85
	v_mov_b32_e32 v99, v97
	v_pk_fma_f32 v[100:101], v[100:101], v[100:101], v[102:103]
	v_mov_b32_e32 v104, v75
	v_mov_b32_e32 v105, v79
	v_pk_fma_f32 v[98:99], v[98:99], v[98:99], v[100:101]
	v_mov_b32_e32 v102, v74
	v_mov_b32_e32 v103, v78
	v_pk_mul_f32 v[104:105], v[104:105], v[104:105]
	v_add_f32_e32 v99, v99, v106
	v_mov_b32_e32 v100, v76
	v_mov_b32_e32 v101, v80
	v_pk_fma_f32 v[102:103], v[102:103], v[102:103], v[104:105]
	v_add_f32_e32 v106, v98, v99
	v_mov_b32_e32 v98, v77
	v_mov_b32_e32 v99, v81
	v_pk_fma_f32 v[100:101], v[100:101], v[100:101], v[102:103]
	s_mov_b32 s19, 0x240f4000
	v_pk_fma_f32 v[98:99], v[98:99], v[98:99], v[100:101]
	s_nop 0
	v_add_f32_e32 v99, v99, v106
	v_add_f32_e32 v98, v98, v99
	ds_bpermute_b32 v99, v227, v98
	s_waitcnt lgkmcnt(0)
	v_add_f32_e32 v98, v98, v99
	ds_bpermute_b32 v99, v228, v98
	s_waitcnt lgkmcnt(0)
	v_add_f32_e32 v98, v98, v99
	ds_bpermute_b32 v99, v229, v98
	s_waitcnt lgkmcnt(0)
	v_add_f32_e32 v98, v98, v99
	ds_bpermute_b32 v99, v230, v98
	s_waitcnt lgkmcnt(0)
	v_add_f32_e32 v98, v98, v99
	ds_bpermute_b32 v99, v231, v98
	s_waitcnt lgkmcnt(0)
	v_add_f32_e32 v98, v98, v99
	ds_bpermute_b32 v99, v232, v98
	s_waitcnt lgkmcnt(0)
	v_add_f32_e32 v98, v98, v99
	v_fmamk_f32 v98, v98, 0x3a000000, v214
	v_mul_f32_e32 v99, 0x4b800000, v98
	v_cmp_gt_f32_e32 vcc, s17, v98
	s_nop 1
	v_cndmask_b32_e32 v98, v98, v99, vcc
	v_rsq_f32_e32 v98, v98
	s_nop 0
	v_mul_f32_e32 v99, 0x45800000, v98
	v_cndmask_b32_e32 v98, v98, v99, vcc
	v_pk_mul_f32 v[86:87], v[86:87], v[98:99] op_sel_hi:[1,0]
	v_pk_mul_f32 v[88:89], v[88:89], v[98:99] op_sel_hi:[1,0]
	v_pk_fma_f32 v[86:87], v[132:133], v[86:87], v[6:7]
	v_pk_fma_f32 v[88:89], v[134:135], v[88:89], v[8:9]
	v_cvt_pk_bf16_f32 v86, v86, v87
	v_cvt_pk_bf16_f32 v87, v88, v89
	v_lshl_add_u64 v[88:89], s[8:9], 0, v[0:1]
	v_pk_mul_f32 v[66:67], v[66:67], v[98:99] op_sel_hi:[1,0]
	v_pk_mul_f32 v[68:69], v[68:69], v[98:99] op_sel_hi:[1,0]
	v_add_co_u32_e32 v100, vcc, s19, v88
	v_pk_fma_f32 v[68:69], v[138:139], v[68:69], v[4:5]
	v_pk_fma_f32 v[66:67], v[136:137], v[66:67], v[2:3]
	v_addc_co_u32_e32 v101, vcc, 0, v89, vcc
	v_cvt_pk_bf16_f32 v66, v66, v67
	v_cvt_pk_bf16_f32 v67, v68, v69
	global_store_dwordx2 v[100:101], v[66:67], off offset:2560
	v_pk_mul_f32 v[66:67], v[70:71], v[98:99] op_sel_hi:[1,0]
	v_pk_mul_f32 v[68:69], v[72:73], v[98:99] op_sel_hi:[1,0]
	v_pk_fma_f32 v[66:67], v[140:141], v[66:67], v[14:15]
	v_pk_fma_f32 v[68:69], v[142:143], v[68:69], v[16:17]
	v_cvt_pk_bf16_f32 v66, v66, v67
	v_cvt_pk_bf16_f32 v67, v68, v69
	global_store_dwordx2 v[100:101], v[66:67], off offset:3072
	v_pk_mul_f32 v[66:67], v[90:91], v[98:99] op_sel_hi:[1,0]
	v_pk_mul_f32 v[68:69], v[92:93], v[98:99] op_sel_hi:[1,0]
	v_pk_fma_f32 v[66:67], v[144:145], v[66:67], v[10:11]
	v_pk_fma_f32 v[68:69], v[146:147], v[68:69], v[12:13]
	v_cvt_pk_bf16_f32 v66, v66, v67
	v_cvt_pk_bf16_f32 v67, v68, v69
	global_store_dwordx2 v[100:101], v[66:67], off offset:3584
	v_pk_mul_f32 v[66:67], v[94:95], v[98:99] op_sel_hi:[1,0]
	v_pk_mul_f32 v[68:69], v[96:97], v[98:99] op_sel_hi:[1,0]
	v_pk_fma_f32 v[66:67], v[148:149], v[66:67], v[22:23]
	v_pk_fma_f32 v[68:69], v[150:151], v[68:69], v[24:25]
	s_mov_b32 s19, 0x240f5000
	v_cvt_pk_bf16_f32 v66, v66, v67
	v_cvt_pk_bf16_f32 v67, v68, v69
	v_add_co_u32_e32 v68, vcc, s19, v88
	v_pk_mul_f32 v[70:71], v[84:85], v[98:99] op_sel_hi:[1,0]
	s_nop 0
	v_addc_co_u32_e32 v69, vcc, 0, v89, vcc
	global_store_dwordx2 v[68:69], v[66:67], off
	v_pk_mul_f32 v[66:67], v[82:83], v[98:99] op_sel_hi:[1,0]
	v_pk_fma_f32 v[70:71], v[154:155], v[70:71], v[20:21]
	v_pk_fma_f32 v[66:67], v[152:153], v[66:67], v[18:19]
	global_store_dwordx2 v[100:101], v[86:87], off offset:2048
	v_cvt_pk_bf16_f32 v66, v66, v67
	v_cvt_pk_bf16_f32 v67, v70, v71
	global_store_dwordx2 v[68:69], v[66:67], off offset:512
	v_pk_mul_f32 v[66:67], v[78:79], v[98:99] op_sel_hi:[1,0]
	v_pk_mul_f32 v[70:71], v[80:81], v[98:99] op_sel_hi:[1,0]
	v_pk_fma_f32 v[66:67], v[156:157], v[66:67], v[30:31]
	v_pk_fma_f32 v[70:71], v[158:159], v[70:71], v[32:33]
	v_cvt_pk_bf16_f32 v66, v66, v67
	v_cvt_pk_bf16_f32 v67, v70, v71
	global_store_dwordx2 v[68:69], v[66:67], off offset:1024
	v_pk_mul_f32 v[66:67], v[74:75], v[98:99] op_sel_hi:[1,0]
	v_pk_mul_f32 v[70:71], v[76:77], v[98:99] op_sel_hi:[1,0]
	v_pk_fma_f32 v[66:67], v[160:161], v[66:67], v[26:27]
	v_pk_fma_f32 v[70:71], v[162:163], v[70:71], v[28:29]
	v_cvt_pk_bf16_f32 v66, v66, v67
	v_cvt_pk_bf16_f32 v67, v70, v71
	global_store_dwordx2 v[68:69], v[66:67], off offset:1536
	s_branch .LBB0_305

; __device__ __forceinline__ void row_coef_load(RowCoef& rc, const float* gA, const float* gate, const float* gB, const float* scale,
;                                               const float* shift, int lane) {
; #pragma unroll
;   for (int i = 0; i < 8; ++i) {
;     const int c = (i * 64 + lane) * 4;
;     rc.cA[i] = f32x4{0.f, 0.f, 0.f, 0.f};
;     rc.cB[i] = f32x4{0.f, 0.f, 0.f, 0.f};
;     rc.cS[i] = f32x4{0.f, 0.f, 0.f, 0.f};
;     if (gA != nullptr) rc.cA[i] = *(const f32x4*)(gA + c) * *(const f32x4*)(gate + c);
;     if (gB != nullptr) {
;       rc.cB[i] = *(const f32x4*)(gB + c) * (*(const f32x4*)(scale + c) + 1.f);
;       rc.cS[i] = *(const f32x4*)(shift + c);
;     }
;   }
; }
; __device__ __forceinline__ void run_phase(const Params& p, int ph, bf16_t* lds, const int wave0) {
;     ...
;     row_coef_load(rc, ng + 3 * 2048, mod + 5 * 2048, last ? nullptr : ngn, last ? nullptr : modn + 2048, last ? nullptr : modn, lane);
;     {
;       RowData cur, nxt;
;       int row = bid * 4 + wave;
;       row_load(cur, p.out + (long)row * 2048, f + (long)row * 2048, lane);
.LBB0_546:
	s_cmp_gt_i32 s39, 5
	s_mov_b64 s[54:55], -1
	s_cbranch_scc0 .LBB0_552
	s_lshl_b32 s0, s33, 2
	s_add_i32 s0, s0, s71
	s_cmpk_gt_i32 s0, 0x3fff
	s_cbranch_scc1 .LBB0_553
	s_cmp_lt_u32 s17, 13
	v_readlane_b32 s4, v253, 16
	v_readlane_b32 s6, v253, 18
	v_readlane_b32 s12, v253, 24
	v_readlane_b32 s13, v253, 25
	v_readlane_b32 s18, v253, 30
	v_readlane_b32 s19, v253, 31
	v_readlane_b32 s7, v253, 19
	s_cselect_b32 s12, s53, s19
	s_cselect_b32 s13, s52, s18
	s_add_u32 s6, s42, 0x2000
	v_readlane_b32 s10, v253, 22
	s_addc_u32 s7, s43, 0
	v_readlane_b32 s11, v253, 23
	s_add_u32 s10, s40, 0x4000
	s_waitcnt vmcnt(0)
	v_lshlrev_b32_e32 v98, 4, v223
	s_addc_u32 s11, s41, 0
	global_load_dwordx4 v[2:5], v98, s[6:7]
	global_load_dwordx4 v[6:9], v98, s[10:11]
	v_readlane_b32 s8, v253, 20
	v_readlane_b32 s9, v253, 21
	s_add_u32 s8, s42, 0x4000
	s_addc_u32 s9, s43, 0
	v_readlane_b32 s5, v253, 17
	s_add_u32 s4, s40, 0x8000
	s_addc_u32 s5, s41, 0
	s_add_u32 s2, s40, 0x6000
	s_addc_u32 s3, s41, 0
	v_or_b32_e32 v0, 0x400, v98
	v_or_b32_e32 v35, 0x1000, v98
	v_or_b32_e32 v40, 0x1400, v98
	v_or_b32_e32 v41, 0x1800, v98
	s_ashr_i32 s1, s0, 31
	v_lshlrev_b32_e32 v34, 2, v223
	v_xor_b32_e32 v196, 0x80, v34
	v_xor_b32_e32 v197, 64, v34
	v_xor_b32_e32 v198, 32, v34
	v_xor_b32_e32 v199, 16, v34
	v_xor_b32_e32 v200, 8, v34
	v_xor_b32_e32 v201, 4, v34
	v_mov_b32_e32 v99, v1
	v_readlane_b32 s14, v253, 26
	v_readlane_b32 s15, v253, 27
	v_readlane_b32 s16, v253, 28
	v_readlane_b32 s17, v253, 29
	s_waitcnt vmcnt(0)
	v_pk_mul_f32 v[100:101], v[4:5], v[8:9]
	v_pk_mul_f32 v[102:103], v[2:3], v[6:7]
	global_load_dwordx4 v[2:5], v98, s[8:9]
	global_load_dwordx4 v[6:9], v98, s[4:5]
	s_waitcnt vmcnt(0)
	v_pk_add_f32 v[8:9], v[8:9], 1.0 op_sel_hi:[1,0]
	v_pk_add_f32 v[6:7], v[6:7], 1.0 op_sel_hi:[1,0]
	v_pk_mul_f32 v[104:105], v[4:5], v[8:9]
	v_pk_mul_f32 v[106:107], v[2:3], v[6:7]
	global_load_dwordx4 v[2:5], v98, s[2:3]
	global_load_dwordx4 v[6:9], v0, s[6:7]
	global_load_dwordx4 v[10:13], v0, s[10:11]
	s_waitcnt vmcnt(0)
	v_pk_mul_f32 v[108:109], v[8:9], v[12:13]
	v_pk_mul_f32 v[110:111], v[6:7], v[10:11]
	global_load_dwordx4 v[6:9], v0, s[8:9]
	global_load_dwordx4 v[10:13], v0, s[4:5]
	s_waitcnt vmcnt(0)
	v_pk_add_f32 v[12:13], v[12:13], 1.0 op_sel_hi:[1,0]
	v_pk_add_f32 v[10:11], v[10:11], 1.0 op_sel_hi:[1,0]
	v_pk_mul_f32 v[112:113], v[8:9], v[12:13]
	v_pk_mul_f32 v[114:115], v[6:7], v[10:11]
	global_load_dwordx4 v[6:9], v0, s[2:3]
	v_or_b32_e32 v0, 0x800, v98
	global_load_dwordx4 v[10:13], v0, s[6:7]
	global_load_dwordx4 v[14:17], v0, s[10:11]
	s_waitcnt vmcnt(0)
	v_pk_mul_f32 v[116:117], v[12:13], v[16:17]
	v_pk_mul_f32 v[118:119], v[10:11], v[14:15]
	global_load_dwordx4 v[10:13], v0, s[8:9]
	global_load_dwordx4 v[14:17], v0, s[4:5]
	s_waitcnt vmcnt(0)
	v_pk_add_f32 v[16:17], v[16:17], 1.0 op_sel_hi:[1,0]
	v_pk_add_f32 v[14:15], v[14:15], 1.0 op_sel_hi:[1,0]
	v_pk_mul_f32 v[120:121], v[12:13], v[16:17]
	v_pk_mul_f32 v[122:123], v[10:11], v[14:15]
	global_load_dwordx4 v[10:13], v0, s[2:3]
	v_or_b32_e32 v0, 0xc00, v98
	global_load_dwordx4 v[14:17], v0, s[6:7]
	global_load_dwordx4 v[18:21], v0, s[10:11]
	s_waitcnt vmcnt(0)
	v_pk_mul_f32 v[124:125], v[16:17], v[20:21]
	v_pk_mul_f32 v[126:127], v[14:15], v[18:19]
	global_load_dwordx4 v[14:17], v0, s[8:9]
	global_load_dwordx4 v[18:21], v0, s[4:5]
	s_waitcnt vmcnt(0)
	v_pk_add_f32 v[20:21], v[20:21], 1.0 op_sel_hi:[1,0]
	v_pk_add_f32 v[18:19], v[18:19], 1.0 op_sel_hi:[1,0]
	v_pk_mul_f32 v[128:129], v[16:17], v[20:21]
	v_pk_mul_f32 v[130:131], v[14:15], v[18:19]
	global_load_dwordx4 v[14:17], v0, s[2:3]
	global_load_dwordx4 v[18:21], v35, s[6:7]
	global_load_dwordx4 v[22:25], v35, s[10:11]
	v_or_b32_e32 v0, 0x1c00, v98
	s_waitcnt vmcnt(0)
	v_pk_mul_f32 v[132:133], v[20:21], v[24:25]
	v_pk_mul_f32 v[134:135], v[18:19], v[22:23]
	global_load_dwordx4 v[18:21], v35, s[8:9]
	global_load_dwordx4 v[22:25], v35, s[4:5]
	s_waitcnt vmcnt(0)
	v_pk_add_f32 v[24:25], v[24:25], 1.0 op_sel_hi:[1,0]
	v_pk_add_f32 v[22:23], v[22:23], 1.0 op_sel_hi:[1,0]
	v_pk_mul_f32 v[136:137], v[20:21], v[24:25]
	v_pk_mul_f32 v[138:139], v[18:19], v[22:23]
	global_load_dwordx4 v[18:21], v35, s[2:3]
	global_load_dwordx4 v[22:25], v40, s[6:7]
	global_load_dwordx4 v[26:29], v40, s[10:11]
	s_waitcnt vmcnt(0)
	v_pk_mul_f32 v[140:141], v[24:25], v[28:29]
	v_pk_mul_f32 v[142:143], v[22:23], v[26:27]
	global_load_dwordx4 v[22:25], v40, s[8:9]
	global_load_dwordx4 v[26:29], v40, s[4:5]
	s_waitcnt vmcnt(0)
	v_pk_add_f32 v[28:29], v[28:29], 1.0 op_sel_hi:[1,0]
	v_pk_add_f32 v[26:27], v[26:27], 1.0 op_sel_hi:[1,0]
	v_pk_mul_f32 v[144:145], v[24:25], v[28:29]
	v_pk_mul_f32 v[146:147], v[22:23], v[26:27]
	global_load_dwordx4 v[22:25], v40, s[2:3]
	global_load_dwordx4 v[26:29], v41, s[6:7]
	global_load_dwordx4 v[30:33], v41, s[10:11]
	s_waitcnt vmcnt(0)
	v_pk_mul_f32 v[148:149], v[28:29], v[32:33]
	v_pk_mul_f32 v[150:151], v[26:27], v[30:31]
	global_load_dwordx4 v[26:29], v41, s[8:9]
	global_load_dwordx4 v[30:33], v41, s[4:5]
	s_waitcnt vmcnt(0)
	v_pk_add_f32 v[32:33], v[32:33], 1.0 op_sel_hi:[1,0]
	v_pk_add_f32 v[30:31], v[30:31], 1.0 op_sel_hi:[1,0]
	v_pk_mul_f32 v[152:153], v[28:29], v[32:33]
	v_pk_mul_f32 v[154:155], v[26:27], v[30:31]
	global_load_dwordx4 v[26:29], v41, s[2:3]
	global_load_dwordx4 v[30:33], v0, s[6:7]
	global_load_dwordx4 v[36:39], v0, s[10:11]
	s_lshl_b64 s[6:7], s[0:1], 13
	s_waitcnt vmcnt(0)
	v_pk_mul_f32 v[156:157], v[32:33], v[38:39]
	v_pk_mul_f32 v[158:159], v[30:31], v[36:37]
	global_load_dwordx4 v[30:33], v0, s[8:9]
	global_load_dwordx4 v[36:39], v0, s[4:5]
	s_add_u32 s4, s13, s6
	s_addc_u32 s5, s12, s7
	global_load_dwordx4 v[42:45], v0, s[4:5]
	s_waitcnt vmcnt(1)
; __device__ __forceinline__ void row_post(const RowData& rd, float* xout, const RowCoef& rc, const bool has_h, bf16_t* hrow, int lane) {
;   f32x4 xv[8], yv[8];
;   float ss = 0.f;
; #pragma unroll
;   for (int i = 0; i < 8; ++i) {
;     const u32x2 yw = rd.y[i];
;     yv[i] = f32x4{__uint_as_float(yw[0] << 16), __uint_as_float(yw[0] & 0xffff0000u), __uint_as_float(yw[1] << 16),
;                   __uint_as_float(yw[1] & 0xffff0000u)};
;     ss += yv[i][0] * yv[i][0] + yv[i][1] * yv[i][1] + yv[i][2] * yv[i][2] + yv[i][3] * yv[i][3];
;   }
;   ss = wave_sum(ss, lane);
; __device__ __forceinline__ void run_phase(const Params& p, int ph, bf16_t* lds, const int wave0) {
;     ...
;       RowData cur, nxt;
;       int row = bid * 4 + wave;
;       row_load(cur, p.out + (long)row * 2048, f + (long)row * 2048, lane);
;       for (; row < S_; row += nb * 4) {
;         const int nrow = row + nb * 4;
;         if (nrow < S_) row_load(nxt, p.out + (long)nrow * 2048, f + (long)nrow * 2048, lane);
;         row_post(cur, p.out + (long)row * 2048, rc, !last, ((bf16_t*)(p.ws + OFF_h)) + (long)row * 2048, lane);
;         cur = nxt;
;       }
	v_pk_add_f32 v[38:39], v[38:39], 1.0 op_sel_hi:[1,0]
	v_pk_add_f32 v[36:37], v[36:37], 1.0 op_sel_hi:[1,0]
	v_pk_mul_f32 v[160:161], v[32:33], v[38:39]
	v_pk_mul_f32 v[162:163], v[30:31], v[36:37]
	global_load_dwordx4 v[30:33], v0, s[2:3]
	s_lshl_b64 s[2:3], s[0:1], 12
	s_add_u32 s8, s86, s2
	s_addc_u32 s9, s87, s3
	v_lshlrev_b32_e32 v0, 3, v223
	global_load_dwordx2 v[180:181], v0, s[8:9] offset:3584
	global_load_dwordx4 v[62:65], v41, s[4:5]
	global_load_dwordx2 v[182:183], v0, s[8:9] offset:3072
	global_load_dwordx4 v[74:77], v40, s[4:5]
	global_load_dwordx2 v[184:185], v0, s[8:9] offset:2560
	global_load_dwordx4 v[78:81], v35, s[4:5]
	global_load_dwordx2 v[186:187], v0, s[8:9] offset:2048
	global_load_dwordx4 v[82:85], v98, s[4:5] offset:3072
	global_load_dwordx2 v[188:189], v0, s[8:9] offset:1536
	global_load_dwordx4 v[86:89], v98, s[4:5] offset:2048
	global_load_dwordx2 v[190:191], v0, s[8:9] offset:1024
	global_load_dwordx4 v[90:93], v98, s[4:5] offset:1024
	global_load_dwordx2 v[192:193], v0, s[8:9] offset:512
	global_load_dwordx4 v[94:97], v98, s[4:5]
	global_load_dwordx2 v[194:195], v0, s[8:9]
	s_add_u32 s2, s84, s2
	s_addc_u32 s3, s85, s3
	s_add_i32 s1, s34, s71
	s_lshl_b32 s4, s70, 3
	s_add_i32 s1, s1, s4
	s_lshl_b32 s4, s38, 2
	s_add_i32 s8, s1, s4
	s_ashr_i32 s9, s8, 31
	s_lshl_b64 s[4:5], s[8:9], 13
	s_add_u32 s4, s13, s4
	s_addc_u32 s5, s12, s5
	s_add_u32 s6, s18, s6
	s_addc_u32 s7, s19, s7
	s_lshl_b64 s[8:9], s[8:9], 12
	s_add_u32 s8, s84, s8
	s_mov_b32 s1, 0x240f4000
	s_addc_u32 s9, s85, s9
	s_waitcnt vmcnt(0)
	s_branch .LBB0_550
.LBB0_549:
	v_and_b32_e32 v203, 0xffff0000, v194
	v_and_b32_e32 v205, 0xffff0000, v192
	v_lshlrev_b32_e32 v202, 16, v194
	v_mul_f32_e32 v206, v203, v203
	v_lshlrev_b32_e32 v204, 16, v192
	v_mul_f32_e32 v207, v205, v205
	v_lshlrev_b32_e32 v194, 16, v195
	v_fmac_f32_e32 v206, v202, v202
	v_lshlrev_b32_e32 v192, 16, v193
	v_fmac_f32_e32 v207, v204, v204
	v_and_b32_e32 v195, 0xffff0000, v195
	v_fmac_f32_e32 v206, v194, v194
	v_and_b32_e32 v193, 0xffff0000, v193
	v_fmac_f32_e32 v207, v192, v192
	v_fmac_f32_e32 v206, v195, v195
	v_fmac_f32_e32 v207, v193, v193
	v_add_f32_e32 v208, v206, v207
	v_and_b32_e32 v207, 0xffff0000, v190
	v_lshlrev_b32_e32 v206, 16, v190
	v_mul_f32_e32 v209, v207, v207
	v_lshlrev_b32_e32 v190, 16, v191
	v_fmac_f32_e32 v209, v206, v206
	v_and_b32_e32 v191, 0xffff0000, v191
	v_fmac_f32_e32 v209, v190, v190
	v_fmac_f32_e32 v209, v191, v191
	v_add_f32_e32 v210, v209, v208
	v_and_b32_e32 v209, 0xffff0000, v188
	v_lshlrev_b32_e32 v208, 16, v188
	v_mul_f32_e32 v211, v209, v209
	v_lshlrev_b32_e32 v188, 16, v189
	v_fmac_f32_e32 v211, v208, v208
	v_and_b32_e32 v189, 0xffff0000, v189
	v_fmac_f32_e32 v211, v188, v188
	v_fmac_f32_e32 v211, v189, v189
	v_and_b32_e32 v219, 0xffff0000, v186
	v_and_b32_e32 v218, 0xffff0000, v184
	v_add_f32_e32 v226, v211, v210
	v_lshlrev_b32_e32 v211, 16, v186
	v_lshlrev_b32_e32 v210, 16, v184
	v_lshlrev_b32_e32 v220, 16, v185
	v_and_b32_e32 v186, 0xffff0000, v185
	v_pk_mul_f32 v[184:185], v[218:219], v[218:219]
	v_lshlrev_b32_e32 v221, 16, v187
	v_pk_fma_f32 v[184:185], v[210:211], v[210:211], v[184:185]
	v_and_b32_e32 v187, 0xffff0000, v187
	v_pk_fma_f32 v[184:185], v[220:221], v[220:221], v[184:185]
	v_and_b32_e32 v227, 0xffff0000, v182
	v_pk_fma_f32 v[184:185], v[186:187], v[186:187], v[184:185]
	v_lshlrev_b32_e32 v228, 16, v181
	v_add_f32_e32 v185, v185, v226
	v_and_b32_e32 v226, 0xffff0000, v180
	v_add_f32_e32 v230, v184, v185
	v_lshlrev_b32_e32 v185, 16, v182
	v_lshlrev_b32_e32 v184, 16, v180
	v_and_b32_e32 v182, 0xffff0000, v181
	v_pk_mul_f32 v[180:181], v[226:227], v[226:227]
	v_lshlrev_b32_e32 v229, 16, v183
	v_pk_fma_f32 v[180:181], v[184:185], v[184:185], v[180:181]
	v_and_b32_e32 v183, 0xffff0000, v183
	v_pk_fma_f32 v[180:181], v[228:229], v[228:229], v[180:181]
	s_mov_b32 s12, 0x240f5000
	v_pk_fma_f32 v[180:181], v[182:183], v[182:183], v[180:181]
	s_nop 0
	v_add_f32_e32 v181, v181, v230
	v_add_f32_e32 v180, v180, v181
	ds_bpermute_b32 v181, v196, v180
	s_waitcnt lgkmcnt(0)
	v_add_f32_e32 v180, v180, v181
	ds_bpermute_b32 v181, v197, v180
	s_waitcnt lgkmcnt(0)
	v_add_f32_e32 v180, v180, v181
	ds_bpermute_b32 v181, v198, v180
	s_waitcnt lgkmcnt(0)
	v_add_f32_e32 v180, v180, v181
	ds_bpermute_b32 v181, v199, v180
	s_waitcnt lgkmcnt(0)
	v_add_f32_e32 v180, v180, v181
	ds_bpermute_b32 v181, v200, v180
	s_waitcnt lgkmcnt(0)
	v_add_f32_e32 v180, v180, v181
	ds_bpermute_b32 v181, v201, v180
	s_waitcnt lgkmcnt(0)
; __device__ __forceinline__ void row_post(const RowData& rd, float* xout, const RowCoef& rc, const bool has_h, bf16_t* hrow, int lane) {
;     ...
;   ss = wave_sum(ss, lane);
;   const float invy = rsqrtf(ss * (1.f / 2048.f) + 1e-6f);
;   float sx = 0.f;
; #pragma unroll
;   for (int i = 0; i < 8; ++i) {
;     const int c = (i * 64 + lane) * 4;
;     const f32x4 xn = rd.x[i] + (yv[i] * invy) * rc.cA[i];
;     xv[i] = xn;
;     *(f32x4*)(xout + c) = xn;
;     sx += xn[0] * xn[0] + xn[1] * xn[1] + xn[2] * xn[2] + xn[3] * xn[3];
;   }
;   if (has_h) {
;     sx = wave_sum(sx, lane);
;     const float inv = rsqrtf(sx * (1.f / 2048.f) + 1e-6f);
	v_add_f32_e32 v180, v180, v181
	v_fmamk_f32 v180, v180, 0x3a000000, v214
	v_mul_f32_e32 v181, 0x4b800000, v180
	v_cmp_gt_f32_e32 vcc, s35, v180
	s_nop 1
	v_cndmask_b32_e32 v180, v180, v181, vcc
	v_rsq_f32_e32 v180, v180
	s_nop 0
	v_mul_f32_e32 v181, 0x45800000, v180
	v_cndmask_b32_e32 v180, v180, v181, vcc
	v_pk_mul_f32 v[190:191], v[190:191], v[180:181] op_sel_hi:[1,0]
	v_pk_mul_f32 v[188:189], v[188:189], v[180:181] op_sel_hi:[1,0]
	v_pk_fma_f32 v[88:89], v[116:117], v[190:191], v[88:89]
	v_pk_mul_f32 v[190:191], v[208:209], v[180:181] op_sel_hi:[1,0]
	v_pk_fma_f32 v[84:85], v[124:125], v[188:189], v[84:85]
	v_mov_b32_e32 v188, v211
	v_mov_b32_e32 v189, v219
	v_pk_fma_f32 v[82:83], v[126:127], v[190:191], v[82:83]
	v_pk_mul_f32 v[188:189], v[188:189], v[180:181] op_sel_hi:[1,0]
	v_mov_b32_e32 v190, v221
	v_mov_b32_e32 v211, v218
	v_mov_b32_e32 v221, v186
	v_pk_mul_f32 v[194:195], v[194:195], v[180:181] op_sel_hi:[1,0]
	v_mov_b32_e32 v191, v187
	v_pk_fma_f32 v[78:79], v[134:135], v[188:189], v[78:79]
	v_pk_mul_f32 v[188:189], v[210:211], v[180:181] op_sel_hi:[1,0]
	v_pk_mul_f32 v[186:187], v[220:221], v[180:181] op_sel_hi:[1,0]
	v_pk_mul_f32 v[202:203], v[202:203], v[180:181] op_sel_hi:[1,0]
	v_pk_fma_f32 v[96:97], v[100:101], v[194:195], v[96:97]
	v_pk_mul_f32 v[192:193], v[192:193], v[180:181] op_sel_hi:[1,0]
	v_pk_mul_f32 v[194:195], v[204:205], v[180:181] op_sel_hi:[1,0]
	v_pk_fma_f32 v[76:77], v[140:141], v[186:187], v[76:77]
	v_pk_fma_f32 v[74:75], v[142:143], v[188:189], v[74:75]
	v_mov_b32_e32 v186, v185
	v_mov_b32_e32 v187, v227
	v_mov_b32_e32 v188, v229
	v_mov_b32_e32 v189, v183
	v_mov_b32_e32 v185, v226
	v_mov_b32_e32 v229, v182
	v_pk_fma_f32 v[94:95], v[102:103], v[202:203], v[94:95]
	v_pk_fma_f32 v[90:91], v[110:111], v[194:195], v[90:91]
	v_pk_fma_f32 v[92:93], v[108:109], v[192:193], v[92:93]
	v_pk_mul_f32 v[192:193], v[206:207], v[180:181] op_sel_hi:[1,0]
	v_pk_mul_f32 v[190:191], v[190:191], v[180:181] op_sel_hi:[1,0]
	v_pk_mul_f32 v[186:187], v[186:187], v[180:181] op_sel_hi:[1,0]
	v_pk_mul_f32 v[188:189], v[188:189], v[180:181] op_sel_hi:[1,0]
	v_pk_mul_f32 v[184:185], v[184:185], v[180:181] op_sel_hi:[1,0]
	v_pk_mul_f32 v[180:181], v[228:229], v[180:181] op_sel_hi:[1,0]
	v_pk_fma_f32 v[86:87], v[118:119], v[192:193], v[86:87]
	v_pk_fma_f32 v[44:45], v[156:157], v[180:181], v[44:45]
	v_mul_f32_e32 v180, v95, v95
	v_mul_f32_e32 v181, v91, v91
	v_fmac_f32_e32 v180, v94, v94
	v_fmac_f32_e32 v181, v90, v90
	v_fmac_f32_e32 v180, v96, v96
	v_fmac_f32_e32 v181, v92, v92
	v_fmac_f32_e32 v180, v97, v97
	v_fmac_f32_e32 v181, v93, v93
	v_add_f32_e32 v180, v180, v181
	v_mul_f32_e32 v181, v87, v87
	v_fmac_f32_e32 v181, v86, v86
	v_fmac_f32_e32 v181, v88, v88
	v_fmac_f32_e32 v181, v89, v89
	v_add_f32_e32 v180, v181, v180
	v_mul_f32_e32 v181, v83, v83
	v_pk_fma_f32 v[62:63], v[150:151], v[186:187], v[62:63]
	v_fmac_f32_e32 v181, v82, v82
	v_mov_b32_e32 v186, v75
	v_mov_b32_e32 v187, v79
	v_pk_fma_f32 v[80:81], v[132:133], v[190:191], v[80:81]
	v_pk_fma_f32 v[42:43], v[158:159], v[184:185], v[42:43]
	v_fmac_f32_e32 v181, v84, v84
	v_mov_b32_e32 v184, v74
	v_mov_b32_e32 v185, v78
	v_pk_mul_f32 v[186:187], v[186:187], v[186:187]
	v_fmac_f32_e32 v181, v85, v85
	v_mov_b32_e32 v182, v76
	v_mov_b32_e32 v183, v80
	v_pk_fma_f32 v[184:185], v[184:185], v[184:185], v[186:187]
	v_pk_fma_f32 v[64:65], v[148:149], v[188:189], v[64:65]
	v_add_f32_e32 v188, v181, v180
	v_mov_b32_e32 v180, v77
	v_mov_b32_e32 v181, v81
	v_pk_fma_f32 v[182:183], v[182:183], v[182:183], v[184:185]
	v_mov_b32_e32 v186, v43
	v_mov_b32_e32 v187, v63
	v_pk_fma_f32 v[180:181], v[180:181], v[180:181], v[182:183]
	v_mov_b32_e32 v184, v42
	v_mov_b32_e32 v185, v62
	v_pk_mul_f32 v[186:187], v[186:187], v[186:187]
	v_add_f32_e32 v181, v181, v188
	v_mov_b32_e32 v182, v44
	v_mov_b32_e32 v183, v64
	v_pk_fma_f32 v[184:185], v[184:185], v[184:185], v[186:187]
	v_add_f32_e32 v188, v180, v181
	v_mov_b32_e32 v180, v45
	v_mov_b32_e32 v181, v65
	v_pk_fma_f32 v[182:183], v[182:183], v[182:183], v[184:185]
	v_pk_fma_f32 v[180:181], v[180:181], v[180:181], v[182:183]
	v_add_f32_e32 v181, v181, v188
	v_add_f32_e32 v180, v180, v181
	ds_bpermute_b32 v181, v196, v180
	s_waitcnt lgkmcnt(0)
	v_add_f32_e32 v180, v180, v181
	ds_bpermute_b32 v181, v197, v180
	s_waitcnt lgkmcnt(0)
	v_add_f32_e32 v180, v180, v181
	ds_bpermute_b32 v181, v198, v180
	s_waitcnt lgkmcnt(0)
	v_add_f32_e32 v182, v180, v181
	ds_bpermute_b32 v183, v199, v182
	v_lshl_add_u64 v[180:181], s[6:7], 0, v[98:99]
	global_store_dwordx4 v[180:181], v[94:97], off
	global_store_dwordx4 v[180:181], v[90:93], off offset:1024
	global_store_dwordx4 v[180:181], v[86:89], off offset:2048
	global_store_dwordx4 v[180:181], v[82:85], off offset:3072
	v_add_co_u32_e32 v180, vcc, s26, v180
	s_waitcnt lgkmcnt(0)
; __device__ __forceinline__ void row_post(const RowData& rd, float* xout, const RowCoef& rc, const bool has_h, bf16_t* hrow, int lane) {
;     ...
;   if (has_h) {
;     sx = wave_sum(sx, lane);
;     const float inv = rsqrtf(sx * (1.f / 2048.f) + 1e-6f);
; #pragma unroll
;     for (int i = 0; i < 8; ++i) {
;       const int c = (i * 64 + lane) * 4;
;       const f32x4 hv = xv[i] * inv * rc.cB[i] + rc.cS[i];
;       u32x2 w;
;       w[0] = pack2(hv[0], hv[1]);
;       w[1] = pack2(hv[2], hv[3]);
;       *(u32x2*)(hrow + c) = w;
;     }
;   }
; __device__ __forceinline__ void run_phase(const Params& p, int ph, bf16_t* lds, const int wave0) {
;     ...
;       for (; row < S_; row += nb * 4) {
;         const int nrow = row + nb * 4;
;         if (nrow < S_) row_load(nxt, p.out + (long)nrow * 2048, f + (long)nrow * 2048, lane);
;         row_post(cur, p.out + (long)row * 2048, rc, !last, ((bf16_t*)(p.ws + OFF_h)) + (long)row * 2048, lane);
;         cur = nxt;
;       }
	v_add_f32_e32 v182, v182, v183
	ds_bpermute_b32 v183, v200, v182
	v_addc_co_u32_e32 v181, vcc, 0, v181, vcc
	global_store_dwordx4 v[180:181], v[78:81], off
	global_store_dwordx4 v[180:181], v[74:77], off offset:1024
	global_store_dwordx4 v[180:181], v[62:65], off offset:2048
	global_store_dwordx4 v[180:181], v[42:45], off offset:3072
	s_waitcnt lgkmcnt(0)
	v_add_f32_e32 v182, v182, v183
	ds_bpermute_b32 v183, v201, v182
	s_waitcnt lgkmcnt(0)
	v_add_f32_e32 v182, v182, v183
	v_fmamk_f32 v182, v182, 0x3a000000, v214
	v_mul_f32_e32 v183, 0x4b800000, v182
	v_cmp_gt_f32_e32 vcc, s35, v182
	s_nop 1
	v_cndmask_b32_e32 v182, v182, v183, vcc
	v_rsq_f32_e32 v182, v182
	s_nop 0
	v_mul_f32_e32 v180, 0x45800000, v182
	v_cndmask_b32_e32 v180, v182, v180, vcc
	v_pk_mul_f32 v[94:95], v[94:95], v[180:181] op_sel_hi:[1,0]
	v_pk_mul_f32 v[96:97], v[96:97], v[180:181] op_sel_hi:[1,0]
	v_pk_fma_f32 v[94:95], v[106:107], v[94:95], v[2:3]
	v_pk_fma_f32 v[96:97], v[104:105], v[96:97], v[4:5]
	v_cvt_pk_bf16_f32 v94, v94, v95
	v_cvt_pk_bf16_f32 v95, v96, v97
	v_lshl_add_u64 v[96:97], s[2:3], 0, v[0:1]
	s_add_u32 s2, s2, s22
	s_addc_u32 s3, s3, s23
	v_add_co_u32_e32 v182, vcc, s1, v96
	v_pk_mul_f32 v[78:79], v[78:79], v[180:181] op_sel_hi:[1,0]
	v_pk_mul_f32 v[80:81], v[80:81], v[180:181] op_sel_hi:[1,0]
	s_add_u32 s4, s4, s24
	v_addc_co_u32_e32 v183, vcc, 0, v97, vcc
	v_pk_mul_f32 v[90:91], v[90:91], v[180:181] op_sel_hi:[1,0]
	v_pk_mul_f32 v[92:93], v[92:93], v[180:181] op_sel_hi:[1,0]
	v_pk_mul_f32 v[86:87], v[86:87], v[180:181] op_sel_hi:[1,0]
	v_pk_mul_f32 v[88:89], v[88:89], v[180:181] op_sel_hi:[1,0]
	v_pk_mul_f32 v[82:83], v[82:83], v[180:181] op_sel_hi:[1,0]
	v_pk_mul_f32 v[84:85], v[84:85], v[180:181] op_sel_hi:[1,0]
	v_pk_fma_f32 v[80:81], v[136:137], v[80:81], v[20:21]
	v_pk_fma_f32 v[78:79], v[138:139], v[78:79], v[18:19]
	v_pk_mul_f32 v[74:75], v[74:75], v[180:181] op_sel_hi:[1,0]
	v_pk_mul_f32 v[76:77], v[76:77], v[180:181] op_sel_hi:[1,0]
	v_pk_mul_f32 v[62:63], v[62:63], v[180:181] op_sel_hi:[1,0]
	v_pk_mul_f32 v[64:65], v[64:65], v[180:181] op_sel_hi:[1,0]
	v_pk_mul_f32 v[42:43], v[42:43], v[180:181] op_sel_hi:[1,0]
	v_pk_mul_f32 v[44:45], v[44:45], v[180:181] op_sel_hi:[1,0]
	s_addc_u32 s5, s5, s25
	v_pk_fma_f32 v[92:93], v[112:113], v[92:93], v[8:9]
	v_pk_fma_f32 v[90:91], v[114:115], v[90:91], v[6:7]
	v_pk_fma_f32 v[88:89], v[120:121], v[88:89], v[12:13]
	v_pk_fma_f32 v[86:87], v[122:123], v[86:87], v[10:11]
	v_pk_fma_f32 v[84:85], v[128:129], v[84:85], v[16:17]
	v_pk_fma_f32 v[82:83], v[130:131], v[82:83], v[14:15]
	v_cvt_pk_bf16_f32 v78, v78, v79
	v_cvt_pk_bf16_f32 v79, v80, v81
	v_add_co_u32_e32 v80, vcc, s12, v96
	v_pk_fma_f32 v[76:77], v[144:145], v[76:77], v[24:25]
	v_pk_fma_f32 v[74:75], v[146:147], v[74:75], v[22:23]
	v_pk_fma_f32 v[64:65], v[152:153], v[64:65], v[28:29]
	v_pk_fma_f32 v[62:63], v[154:155], v[62:63], v[26:27]
	v_pk_fma_f32 v[44:45], v[160:161], v[44:45], v[32:33]
	v_pk_fma_f32 v[42:43], v[162:163], v[42:43], v[30:31]
	s_add_u32 s6, s6, s24
	v_cvt_pk_bf16_f32 v90, v90, v91
	v_cvt_pk_bf16_f32 v91, v92, v93
	v_cvt_pk_bf16_f32 v86, v86, v87
	v_cvt_pk_bf16_f32 v87, v88, v89
	v_cvt_pk_bf16_f32 v82, v82, v83
	v_cvt_pk_bf16_f32 v83, v84, v85
	v_addc_co_u32_e32 v81, vcc, 0, v97, vcc
	v_cvt_pk_bf16_f32 v74, v74, v75
	v_cvt_pk_bf16_f32 v75, v76, v77
	v_cvt_pk_bf16_f32 v62, v62, v63
	v_cvt_pk_bf16_f32 v63, v64, v65
	v_cvt_pk_bf16_f32 v42, v42, v43
	v_cvt_pk_bf16_f32 v43, v44, v45
	s_addc_u32 s7, s7, s25
	global_store_dwordx2 v[182:183], v[94:95], off offset:2048
	global_store_dwordx2 v[182:183], v[90:91], off offset:2560
	global_store_dwordx2 v[182:183], v[86:87], off offset:3072
	global_store_dwordx2 v[182:183], v[82:83], off offset:3584
	global_store_dwordx2 v[80:81], v[78:79], off
	global_store_dwordx2 v[80:81], v[74:75], off offset:512
	global_store_dwordx2 v[80:81], v[62:63], off offset:1024
	global_store_dwordx2 v[80:81], v[42:43], off offset:1536
	s_add_u32 s8, s8, s22
	s_waitcnt vmcnt(16)
	v_mov_b64_e32 v[194:195], v[164:165]
	v_mov_b64_e32 v[192:193], v[166:167]
	v_mov_b64_e32 v[190:191], v[168:169]
	v_mov_b64_e32 v[188:189], v[170:171]
	v_mov_b64_e32 v[186:187], v[172:173]
	v_mov_b64_e32 v[184:185], v[174:175]
	v_mov_b64_e32 v[96:97], v[36:37]
	v_mov_b64_e32 v[92:93], v[40:41]
	v_mov_b64_e32 v[88:89], v[48:49]
	v_mov_b64_e32 v[84:85], v[52:53]
	v_mov_b64_e32 v[80:81], v[56:57]
	v_mov_b64_e32 v[76:77], v[60:61]
	v_mov_b64_e32 v[62:63], v[66:67]
	v_mov_b64_e32 v[42:43], v[70:71]
	s_addc_u32 s9, s9, s23
	s_and_b64 vcc, exec, s[10:11]
	v_mov_b64_e32 v[94:95], v[34:35]
	v_mov_b64_e32 v[90:91], v[38:39]
	v_mov_b64_e32 v[86:87], v[46:47]
	v_mov_b64_e32 v[82:83], v[50:51]
	v_mov_b64_e32 v[78:79], v[54:55]
	v_mov_b64_e32 v[74:75], v[58:59]
	v_mov_b64_e32 v[64:65], v[68:69]
	v_mov_b64_e32 v[44:45], v[72:73]
	v_mov_b64_e32 v[182:183], v[176:177]
	v_mov_b64_e32 v[180:181], v[178:179]
	s_cbranch_vccnz .LBB0_553
